# v32 + code placement A/B: the four GEMM loop heads padded with s_nop to 64-byte alignment
# baseline (speedup 1.0000x reference)
.LBB0_395:
	s_add_i32 s66, s66, 1
	s_mov_b64 s[36:37], s[20:21]
	s_mul_i32 s20, s66, s26
	s_add_i32 s42, s20, s2
	s_cmpk_gt_i32 s42, 0x3ff
	s_cselect_b64 s[52:53], -1, 0
	s_lshl_b32 s20, s42, 3
	s_and_b32 s20, s20, 56
	s_bfe_u32 s21, s42, 0x30003
	s_mov_b32 s3, s67
	s_or_b32 s67, s20, s21
	s_mov_b32 s27, s50
	s_ashr_i32 s50, s42, 6
	s_lshl_b32 s20, s67, 19
	s_mov_b64 s[4:5], s[48:49]
	s_add_u32 s48, s18, s20
	s_addc_u32 s49, s19, 0
	s_ashr_i32 s51, s50, 31
	s_lshl_b64 s[20:21], s[50:51], 19
	s_add_u32 s20, s16, s20
	s_addc_u32 s21, s17, s21
	s_cmpk_lt_i32 s42, 0x400
	s_cselect_b32 s46, s49, s5
	s_cselect_b32 s47, s48, s4
	s_cselect_b32 s51, s21, s37
	s_cselect_b32 s54, s20, s36
	s_add_u32 s55, s36, 0x100
	s_addc_u32 s56, s37, 0
	s_mov_b32 s57, -2
	s_add_u32 s36, s4, 0x100
	s_addc_u32 s37, s5, 0
	s_add_i32 s68, 0, 0x10000
	v_add_u32_e32 v30, s68, v204
	ds_read_b128 v[14:17], v30
	ds_read_b128 v[22:25], v30 offset:1024
	ds_read_b128 v[26:29], v30 offset:2048
	ds_read_b128 v[30:33], v30 offset:3072
	s_cmp_eq_u32 s57, 12
	s_cselect_b32 s45, s46, s37
	s_cselect_b32 s44, s47, s36
	s_cselect_b32 s43, s51, s56
	s_cselect_b32 s42, s54, s55
	v_lshl_add_u64 v[178:179], s[4:5], 0, v[188:189]
	s_add_i32 m0, s60, 0xc000
	ds_read_b128 v[38:41], v209
	ds_read_b128 v[42:45], v209 offset:1024
	ds_read_b128 v[46:49], v209 offset:2048
	ds_read_b128 v[54:57], v209 offset:3072
	ds_read_b128 v[58:61], v209 offset:4096
	ds_read_b128 v[62:65], v209 offset:5120
	ds_read_b128 v[66:69], v209 offset:6144
	ds_read_b128 v[70:73], v209 offset:7168
	global_load_lds_dwordx4 v[178:179], off
	v_lshl_add_u64 v[178:179], s[4:5], 0, v[186:187]
	s_add_i32 m0, s60, 0xe000
	s_nop 0
	global_load_lds_dwordx4 v[178:179], off
	s_waitcnt lgkmcnt(8)
	s_barrier
	s_waitcnt lgkmcnt(0)
	s_waitcnt lgkmcnt(0)
	v_mfma_f32_16x16x32_bf16 v[174:177], v[14:17], v[38:41], 0
	v_mfma_f32_16x16x32_bf16 v[170:173], v[26:29], v[38:41], 0
	v_mfma_f32_16x16x32_bf16 v[158:161], v[14:17], v[46:49], 0
	v_mfma_f32_16x16x32_bf16 v[154:157], v[26:29], v[46:49], 0
	v_mfma_f32_16x16x32_bf16 v[142:145], v[14:17], v[58:61], 0
	v_mfma_f32_16x16x32_bf16 v[138:141], v[26:29], v[58:61], 0
	v_mfma_f32_16x16x32_bf16 v[126:129], v[14:17], v[66:69], 0
	v_mfma_f32_16x16x32_bf16 v[122:125], v[26:29], v[66:69], 0
	v_mfma_f32_16x16x32_bf16 v[174:177], v[22:25], v[42:45], v[174:177]
	v_mfma_f32_16x16x32_bf16 v[170:173], v[30:33], v[42:45], v[170:173]
	v_mfma_f32_16x16x32_bf16 v[158:161], v[22:25], v[54:57], v[158:161]
	v_mfma_f32_16x16x32_bf16 v[154:157], v[30:33], v[54:57], v[154:157]
	v_mfma_f32_16x16x32_bf16 v[142:145], v[22:25], v[62:65], v[142:145]
	v_mfma_f32_16x16x32_bf16 v[138:141], v[30:33], v[62:65], v[138:141]
	v_mfma_f32_16x16x32_bf16 v[126:129], v[22:25], v[70:73], v[126:129]
	v_mfma_f32_16x16x32_bf16 v[122:125], v[30:33], v[70:73], v[122:125]
	s_barrier
	v_mbcnt_lo_u32_b32 v250, -1, 0
	v_mbcnt_hi_u32_b32 v250, -1, v250
	v_lshlrev_b32_e32 v250, 4, v250
	s_lshl_b32 s32, s27, 10
	s_add_u32 s90, s10, s32
	s_addc_u32 s91, s11, 0
	s_add_u32 s92, s12, s32
	s_addc_u32 s93, s13, 0
	s_and_b32 s32, s27, 3
	s_lshl_b32 s32, s32, 10
	s_add_u32 s98, s14, s32
	s_addc_u32 s99, s15, 0
	s_mov_b32 m0, 0x20840
	s_nop 0
	global_load_lds_dwordx4 v250, s[90:91]
	s_mov_b32 m0, 0x20c40
	s_nop 0
	global_load_lds_dwordx4 v250, s[92:93]
	s_mov_b32 m0, 0x21040
	s_nop 0
	global_load_lds_dwordx4 v250, s[98:99]
	s_add_i32 s69, 0, 0x14000
	v_add_u32_e32 v210, s69, v204
	s_add_i32 s4, s68, s59
	ds_read_b128 v[178:181], v210
	ds_read_b128 v[190:193], v210 offset:1024
	ds_read_b128 v[200:203], v210 offset:2048
	ds_read_b128 v[222:225], v210 offset:3072
	v_lshl_add_u64 v[210:211], s[42:43], 0, v[184:185]
	s_mov_b32 m0, s4
	v_lshl_add_u64 v[214:215], s[42:43], 0, v[182:183]
	global_load_lds_dwordx4 v[210:211], off
	s_add_i32 m0, s4, 0x2000
	s_nop 0
	global_load_lds_dwordx4 v[214:215], off
	s_barrier
	s_waitcnt lgkmcnt(0)
	s_waitcnt lgkmcnt(0)
	v_mfma_f32_16x16x32_bf16 v[166:169], v[178:181], v[38:41], 0
	v_mfma_f32_16x16x32_bf16 v[38:41], v[200:203], v[38:41], 0
	v_mfma_f32_16x16x32_bf16 v[166:169], v[190:193], v[42:45], v[166:169]
	v_mfma_f32_16x16x32_bf16 v[38:41], v[222:225], v[42:45], v[38:41]
	v_mfma_f32_16x16x32_bf16 v[42:45], v[178:181], v[46:49], 0
	v_mfma_f32_16x16x32_bf16 v[46:49], v[200:203], v[46:49], 0
	v_mfma_f32_16x16x32_bf16 v[42:45], v[190:193], v[54:57], v[42:45]
	v_mfma_f32_16x16x32_bf16 v[46:49], v[222:225], v[54:57], v[46:49]
	v_mfma_f32_16x16x32_bf16 v[54:57], v[178:181], v[58:61], 0
	v_mfma_f32_16x16x32_bf16 v[58:61], v[200:203], v[58:61], 0
	v_mfma_f32_16x16x32_bf16 v[54:57], v[190:193], v[62:65], v[54:57]
	v_mfma_f32_16x16x32_bf16 v[58:61], v[222:225], v[62:65], v[58:61]
	v_mfma_f32_16x16x32_bf16 v[62:65], v[178:181], v[66:69], 0
	v_mfma_f32_16x16x32_bf16 v[66:69], v[200:203], v[66:69], 0
	v_mfma_f32_16x16x32_bf16 v[62:65], v[190:193], v[70:73], v[62:65]
	v_mfma_f32_16x16x32_bf16 v[66:69], v[222:225], v[70:73], v[66:69]
	s_mov_b32 m0, s60
	v_lshl_add_u64 v[242:243], s[44:45], 0, v[184:185]
	s_barrier
	ds_read_b128 v[70:73], v209 offset:16384
	ds_read_b128 v[114:117], v209 offset:17408
	ds_read_b128 v[118:121], v209 offset:18432
	ds_read_b128 v[130:133], v209 offset:19456
	ds_read_b128 v[134:137], v209 offset:20480
	ds_read_b128 v[146:149], v209 offset:21504
	ds_read_b128 v[150:153], v209 offset:22528
	ds_read_b128 v[162:165], v209 offset:23552
	global_load_lds_dwordx4 v[242:243], off
	v_lshl_add_u64 v[244:245], s[44:45], 0, v[182:183]
	s_mov_b32 m0, s61
	s_nop 0
	global_load_lds_dwordx4 v[244:245], off
	s_barrier
	s_waitcnt lgkmcnt(0)
	s_waitcnt lgkmcnt(0)
	v_mfma_f32_16x16x32_bf16 v[110:113], v[14:17], v[70:73], 0
	v_mfma_f32_16x16x32_bf16 v[106:109], v[26:29], v[70:73], 0
	v_mfma_f32_16x16x32_bf16 v[94:97], v[14:17], v[118:121], 0
	v_mfma_f32_16x16x32_bf16 v[90:93], v[26:29], v[118:121], 0
	v_mfma_f32_16x16x32_bf16 v[78:81], v[14:17], v[134:137], 0
	v_mfma_f32_16x16x32_bf16 v[74:77], v[26:29], v[134:137], 0
	v_mfma_f32_16x16x32_bf16 v[10:13], v[26:29], v[150:153], 0
	v_mfma_f32_16x16x32_bf16 v[110:113], v[22:25], v[114:117], v[110:113]
	v_mfma_f32_16x16x32_bf16 v[106:109], v[30:33], v[114:117], v[106:109]
	v_mfma_f32_16x16x32_bf16 v[94:97], v[22:25], v[130:133], v[94:97]
	v_mfma_f32_16x16x32_bf16 v[90:93], v[30:33], v[130:133], v[90:93]
	v_mfma_f32_16x16x32_bf16 v[78:81], v[22:25], v[146:149], v[78:81]
	v_mfma_f32_16x16x32_bf16 v[74:77], v[30:33], v[146:149], v[74:77]
	v_mfma_f32_16x16x32_bf16 v[14:17], v[14:17], v[150:153], 0
	v_mfma_f32_16x16x32_bf16 v[10:13], v[30:33], v[162:165], v[10:13]
	v_mfma_f32_16x16x32_bf16 v[14:17], v[22:25], v[162:165], v[14:17]
	s_barrier
	s_add_u32 s4, s42, 0x40000
	s_addc_u32 s5, s43, 0
	s_add_i32 s68, s69, s59
	v_lshl_add_u64 v[18:19], s[4:5], 0, v[184:185]
	s_mov_b32 m0, s68
	s_nop 0
	global_load_lds_dwordx4 v[18:19], off
	v_lshl_add_u64 v[18:19], s[4:5], 0, v[182:183]
	s_add_i32 m0, s68, 0x2000
	s_nop 0
	global_load_lds_dwordx4 v[18:19], off
	s_waitcnt vmcnt(6)
	s_barrier
	v_mfma_f32_16x16x32_bf16 v[18:21], v[178:181], v[70:73], 0
	v_mfma_f32_16x16x32_bf16 v[22:25], v[190:193], v[114:117], v[18:21]
	v_mfma_f32_16x16x32_bf16 v[18:21], v[200:203], v[70:73], 0
	v_mfma_f32_16x16x32_bf16 v[26:29], v[222:225], v[114:117], v[18:21]
	v_mfma_f32_16x16x32_bf16 v[18:21], v[178:181], v[118:121], 0
	v_mfma_f32_16x16x32_bf16 v[30:33], v[190:193], v[130:133], v[18:21]
	v_mfma_f32_16x16x32_bf16 v[18:21], v[200:203], v[118:121], 0
	v_mfma_f32_16x16x32_bf16 v[70:73], v[222:225], v[130:133], v[18:21]
	v_mfma_f32_16x16x32_bf16 v[18:21], v[178:181], v[134:137], 0
	v_mfma_f32_16x16x32_bf16 v[50:53], v[190:193], v[146:149], v[18:21]
	v_mfma_f32_16x16x32_bf16 v[18:21], v[200:203], v[134:137], 0
	v_mfma_f32_16x16x32_bf16 v[6:9], v[178:181], v[150:153], 0
	v_mfma_f32_16x16x32_bf16 v[2:5], v[200:203], v[150:153], 0
	v_mfma_f32_16x16x32_bf16 v[34:37], v[222:225], v[146:149], v[18:21]
	v_mfma_f32_16x16x32_bf16 v[6:9], v[190:193], v[162:165], v[6:9]
	v_mfma_f32_16x16x32_bf16 v[2:5], v[222:225], v[162:165], v[2:5]
	s_add_i32 s68, 0, 0x18000
	v_add_u32_e32 v98, s68, v204
	s_barrier
	ds_read_b128 v[18:21], v98
	ds_read_b128 v[82:85], v98 offset:1024
	ds_read_b128 v[86:89], v98 offset:2048
	ds_read_b128 v[98:101], v98 offset:3072
	s_add_u32 s4, s44, 0x40000
	s_addc_u32 s5, s45, 0
	s_mov_b32 m0, s62
	v_lshl_add_u64 v[134:135], s[4:5], 0, v[184:185]
	ds_read_b128 v[102:105], v209 offset:32768
	ds_read_b128 v[114:117], v209 offset:33792
	ds_read_b128 v[118:121], v209 offset:34816
	ds_read_b128 v[130:133], v209 offset:35840
	ds_read_b128 v[178:181], v209 offset:36864
	ds_read_b128 v[190:193], v209 offset:37888
	ds_read_b128 v[200:203], v209 offset:38912
	ds_read_b128 v[222:225], v209 offset:39936
	global_load_lds_dwordx4 v[134:135], off
	v_lshl_add_u64 v[134:135], s[4:5], 0, v[182:183]
	s_mov_b32 m0, s63
	s_nop 0
	global_load_lds_dwordx4 v[134:135], off
	s_waitcnt lgkmcnt(8)
	s_barrier
	s_waitcnt lgkmcnt(0)
	s_waitcnt lgkmcnt(0)
	v_mfma_f32_16x16x32_bf16 v[134:137], v[18:21], v[102:105], v[174:177]
	v_mfma_f32_16x16x32_bf16 v[174:177], v[82:85], v[114:117], v[134:137]
	v_mfma_f32_16x16x32_bf16 v[134:137], v[86:89], v[102:105], v[170:173]
	v_mfma_f32_16x16x32_bf16 v[170:173], v[98:101], v[114:117], v[134:137]
	v_mfma_f32_16x16x32_bf16 v[134:137], v[18:21], v[118:121], v[158:161]
	v_mfma_f32_16x16x32_bf16 v[158:161], v[82:85], v[130:133], v[134:137]
	v_mfma_f32_16x16x32_bf16 v[134:137], v[86:89], v[118:121], v[154:157]
	v_mfma_f32_16x16x32_bf16 v[154:157], v[98:101], v[130:133], v[134:137]
	v_mfma_f32_16x16x32_bf16 v[134:137], v[18:21], v[178:181], v[142:145]
	v_mfma_f32_16x16x32_bf16 v[142:145], v[82:85], v[190:193], v[134:137]
	v_mfma_f32_16x16x32_bf16 v[134:137], v[86:89], v[178:181], v[138:141]
	v_mfma_f32_16x16x32_bf16 v[126:129], v[18:21], v[200:203], v[126:129]
	v_mfma_f32_16x16x32_bf16 v[122:125], v[86:89], v[200:203], v[122:125]
	v_mfma_f32_16x16x32_bf16 v[138:141], v[98:101], v[190:193], v[134:137]
	v_mfma_f32_16x16x32_bf16 v[126:129], v[82:85], v[222:225], v[126:129]
	v_mfma_f32_16x16x32_bf16 v[122:125], v[98:101], v[222:225], v[122:125]
	s_barrier
	s_add_i32 s44, 0, 0x1c000
	v_add_u32_e32 v134, s44, v204
	s_add_i32 s4, s68, s59
	ds_read_b128 v[226:229], v134
	ds_read_b128 v[230:233], v134 offset:1024
	ds_read_b128 v[234:237], v134 offset:2048
	ds_read_b128 v[238:241], v134 offset:3072
	v_lshl_add_u64 v[134:135], v[210:211], 0, s[22:23]
	s_mov_b32 m0, s4
	s_nop 0
	global_load_lds_dwordx4 v[134:135], off
	v_lshl_add_u64 v[134:135], v[214:215], 0, s[22:23]
	s_add_i32 m0, s4, 0x2000
	s_nop 0
	global_load_lds_dwordx4 v[134:135], off
	s_barrier
	s_waitcnt lgkmcnt(0)
	s_waitcnt lgkmcnt(0)
	v_mfma_f32_16x16x32_bf16 v[38:41], v[234:237], v[102:105], v[38:41]
	v_mfma_f32_16x16x32_bf16 v[162:165], v[238:241], v[114:117], v[38:41]
	v_mfma_f32_16x16x32_bf16 v[38:41], v[226:229], v[118:121], v[42:45]
	v_mfma_f32_16x16x32_bf16 v[150:153], v[230:233], v[130:133], v[38:41]
	v_mfma_f32_16x16x32_bf16 v[38:41], v[234:237], v[118:121], v[46:49]
	v_mfma_f32_16x16x32_bf16 v[134:137], v[226:229], v[102:105], v[166:169]
	v_mfma_f32_16x16x32_bf16 v[146:149], v[238:241], v[130:133], v[38:41]
	v_mfma_f32_16x16x32_bf16 v[38:41], v[226:229], v[178:181], v[54:57]
	v_mfma_f32_16x16x32_bf16 v[166:169], v[230:233], v[114:117], v[134:137]
	v_mfma_f32_16x16x32_bf16 v[134:137], v[230:233], v[190:193], v[38:41]
	v_mfma_f32_16x16x32_bf16 v[38:41], v[234:237], v[178:181], v[58:61]
	v_mfma_f32_16x16x32_bf16 v[130:133], v[238:241], v[190:193], v[38:41]
	v_mfma_f32_16x16x32_bf16 v[38:41], v[226:229], v[200:203], v[62:65]
	v_mfma_f32_16x16x32_bf16 v[118:121], v[230:233], v[222:225], v[38:41]
	v_mfma_f32_16x16x32_bf16 v[38:41], v[234:237], v[200:203], v[66:69]
	v_mfma_f32_16x16x32_bf16 v[114:117], v[238:241], v[222:225], v[38:41]
	s_mov_b32 m0, s64
	v_lshl_add_u64 v[102:103], v[242:243], 0, s[22:23]
	s_barrier
	s_nop 2
	ds_read_b128 v[38:41], v209 offset:49152
	ds_read_b128 v[42:45], v209 offset:50176
	ds_read_b128 v[46:49], v209 offset:51200
	ds_read_b128 v[54:57], v209 offset:52224
	ds_read_b128 v[58:61], v209 offset:53248
	ds_read_b128 v[62:65], v209 offset:54272
	ds_read_b128 v[66:69], v209 offset:55296
	ds_read_b128 v[178:181], v209 offset:56320
	global_load_lds_dwordx4 v[102:103], off
	v_lshl_add_u64 v[102:103], v[244:245], 0, s[22:23]
	s_mov_b32 m0, s65
	s_nop 0
	global_load_lds_dwordx4 v[102:103], off
	s_barrier
	s_waitcnt lgkmcnt(0)
	s_waitcnt lgkmcnt(0)
	v_mfma_f32_16x16x32_bf16 v[102:105], v[18:21], v[38:41], v[110:113]
	v_mfma_f32_16x16x32_bf16 v[110:113], v[82:85], v[42:45], v[102:105]
	v_mfma_f32_16x16x32_bf16 v[102:105], v[86:89], v[38:41], v[106:109]
	v_mfma_f32_16x16x32_bf16 v[94:97], v[18:21], v[46:49], v[94:97]
	v_mfma_f32_16x16x32_bf16 v[90:93], v[86:89], v[46:49], v[90:93]
	v_mfma_f32_16x16x32_bf16 v[78:81], v[18:21], v[58:61], v[78:81]
	v_mfma_f32_16x16x32_bf16 v[74:77], v[86:89], v[58:61], v[74:77]
	v_mfma_f32_16x16x32_bf16 v[14:17], v[18:21], v[66:69], v[14:17]
	v_mfma_f32_16x16x32_bf16 v[10:13], v[86:89], v[66:69], v[10:13]
	v_mfma_f32_16x16x32_bf16 v[106:109], v[98:101], v[42:45], v[102:105]
	v_mfma_f32_16x16x32_bf16 v[94:97], v[82:85], v[54:57], v[94:97]
	v_mfma_f32_16x16x32_bf16 v[90:93], v[98:101], v[54:57], v[90:93]
	v_mfma_f32_16x16x32_bf16 v[78:81], v[82:85], v[62:65], v[78:81]
	v_mfma_f32_16x16x32_bf16 v[74:77], v[98:101], v[62:65], v[74:77]
	v_mfma_f32_16x16x32_bf16 v[18:21], v[82:85], v[178:181], v[14:17]
	v_mfma_f32_16x16x32_bf16 v[10:13], v[98:101], v[178:181], v[10:13]
	s_barrier
	s_add_u32 s4, s42, 0x40080
	s_addc_u32 s5, s43, 0
	s_add_i32 s42, s44, s59
	v_lshl_add_u64 v[14:15], s[4:5], 0, v[184:185]
	s_mov_b32 m0, s42
	s_nop 0
	global_load_lds_dwordx4 v[14:15], off
	v_lshl_add_u64 v[14:15], s[4:5], 0, v[182:183]
	s_add_i32 m0, s42, 0x2000
	s_nop 0
	global_load_lds_dwordx4 v[14:15], off
	s_waitcnt vmcnt(6)
	s_barrier
	v_mfma_f32_16x16x32_bf16 v[14:17], v[226:229], v[38:41], v[22:25]
	v_mfma_f32_16x16x32_bf16 v[102:105], v[230:233], v[42:45], v[14:17]
	v_mfma_f32_16x16x32_bf16 v[14:17], v[234:237], v[38:41], v[26:29]
	v_mfma_f32_16x16x32_bf16 v[98:101], v[238:241], v[42:45], v[14:17]
	v_mfma_f32_16x16x32_bf16 v[14:17], v[226:229], v[46:49], v[30:33]
	v_mfma_f32_16x16x32_bf16 v[86:89], v[230:233], v[54:57], v[14:17]
	v_mfma_f32_16x16x32_bf16 v[14:17], v[234:237], v[46:49], v[70:73]
	v_mfma_f32_16x16x32_bf16 v[82:85], v[238:241], v[54:57], v[14:17]
	v_mfma_f32_16x16x32_bf16 v[14:17], v[226:229], v[58:61], v[50:53]
	v_mfma_f32_16x16x32_bf16 v[50:53], v[230:233], v[62:65], v[14:17]
	v_mfma_f32_16x16x32_bf16 v[14:17], v[234:237], v[58:61], v[34:37]
	v_mfma_f32_16x16x32_bf16 v[6:9], v[226:229], v[66:69], v[6:9]
	v_mfma_f32_16x16x32_bf16 v[2:5], v[234:237], v[66:69], v[2:5]
	v_mfma_f32_16x16x32_bf16 v[34:37], v[238:241], v[62:65], v[14:17]
	v_mfma_f32_16x16x32_bf16 v[6:9], v[230:233], v[178:181], v[6:9]
	v_mfma_f32_16x16x32_bf16 v[2:5], v[238:241], v[178:181], v[2:5]
	s_add_i32 s57, s57, 2
	s_add_u32 s55, s55, 0x100
	s_addc_u32 s56, s56, 0
	s_cmp_gt_u32 s57, 13
	s_mov_b64 s[4:5], s[36:37]
	s_barrier
	s_nop 0
	s_nop 0

.LBB0_1098:
	s_add_i32 s76, s76, 1
	s_mov_b64 s[62:63], s[54:55]
	s_mul_i32 s54, s76, s26
	s_add_i32 s64, s54, s2
	s_cmpk_gt_i32 s64, 0x57f
	s_cselect_b64 s[60:61], -1, 0
	s_lshl_b32 s54, s64, 3
	s_and_b32 s54, s54, 56
	s_bfe_u32 s55, s64, 0x30003
	s_or_b32 s77, s54, s55
	s_ashr_i32 s58, s64, 6
	s_lshl_b32 s54, s77, 19
	s_mov_b64 s[36:37], s[56:57]
	s_add_u32 s56, s52, s54
	s_addc_u32 s57, s53, 0
	s_ashr_i32 s59, s58, 31
	s_lshl_b64 s[54:55], s[58:59], 19
	s_add_u32 s54, s4, s54
	s_addc_u32 s55, s5, s55
	s_cmpk_lt_i32 s64, 0x580
	s_cselect_b32 s59, s57, s37
	s_cselect_b32 s78, s56, s36
	s_cselect_b32 s79, s55, s63
	s_cselect_b32 s80, s54, s62
	s_add_u32 s81, s62, 0x100
	s_addc_u32 s82, s63, 0
	s_mov_b32 s83, -2
	s_add_u32 s62, s36, 0x100
	s_addc_u32 s63, s37, 0
	s_add_i32 s84, 0, 0x10000
	v_add_u32_e32 v70, s84, v170
	ds_read_b128 v[58:61], v70
	ds_read_b128 v[62:65], v70 offset:1024
	ds_read_b128 v[66:69], v70 offset:2048
	ds_read_b128 v[70:73], v70 offset:3072
	s_cmp_eq_u32 s83, 12
	s_cselect_b32 s67, s59, s63
	s_cselect_b32 s66, s78, s62
	s_cselect_b32 s65, s79, s82
	s_cselect_b32 s64, s80, s81
	v_lshl_add_u64 v[192:193], s[36:37], 0, v[168:169]
	s_add_i32 m0, s69, 0xc000
	ds_read_b128 v[78:81], v175
	ds_read_b128 v[86:89], v175 offset:1024
	ds_read_b128 v[90:93], v175 offset:2048
	ds_read_b128 v[94:97], v175 offset:3072
	ds_read_b128 v[176:179], v175 offset:4096
	ds_read_b128 v[180:183], v175 offset:5120
	ds_read_b128 v[184:187], v175 offset:6144
	ds_read_b128 v[188:191], v175 offset:7168
	global_load_lds_dwordx4 v[192:193], off
	v_lshl_add_u64 v[192:193], s[36:37], 0, v[166:167]
	s_add_i32 m0, s69, 0xe000
	s_nop 0
	global_load_lds_dwordx4 v[192:193], off
	s_waitcnt lgkmcnt(8)
	s_barrier
	s_waitcnt lgkmcnt(0)
	s_waitcnt lgkmcnt(0)
	v_mfma_f32_16x16x32_bf16 v[158:161], v[58:61], v[78:81], 0
	v_mfma_f32_16x16x32_bf16 v[150:153], v[66:69], v[78:81], 0
	v_mfma_f32_16x16x32_bf16 v[142:145], v[58:61], v[90:93], 0
	v_mfma_f32_16x16x32_bf16 v[134:137], v[66:69], v[90:93], 0
	v_mfma_f32_16x16x32_bf16 v[126:129], v[58:61], v[176:179], 0
	v_mfma_f32_16x16x32_bf16 v[118:121], v[66:69], v[176:179], 0
	v_mfma_f32_16x16x32_bf16 v[110:113], v[58:61], v[184:187], 0
	v_mfma_f32_16x16x32_bf16 v[102:105], v[66:69], v[184:187], 0
	v_mfma_f32_16x16x32_bf16 v[158:161], v[62:65], v[86:89], v[158:161]
	v_mfma_f32_16x16x32_bf16 v[150:153], v[70:73], v[86:89], v[150:153]
	v_mfma_f32_16x16x32_bf16 v[142:145], v[62:65], v[94:97], v[142:145]
	v_mfma_f32_16x16x32_bf16 v[134:137], v[70:73], v[94:97], v[134:137]
	v_mfma_f32_16x16x32_bf16 v[126:129], v[62:65], v[180:183], v[126:129]
	v_mfma_f32_16x16x32_bf16 v[118:121], v[70:73], v[180:183], v[118:121]
	v_mfma_f32_16x16x32_bf16 v[110:113], v[62:65], v[188:191], v[110:113]
	v_mfma_f32_16x16x32_bf16 v[102:105], v[70:73], v[188:191], v[102:105]
	s_barrier
	v_mbcnt_lo_u32_b32 v250, -1, 0
	v_mbcnt_hi_u32_b32 v250, -1, v250
	v_lshlrev_b32_e32 v250, 4, v250
	s_lshl_b32 s32, s27, 10
	s_add_u32 s90, s46, s32
	s_addc_u32 s91, s47, 0
	s_add_u32 s92, s48, s32
	s_addc_u32 s93, s49, 0
	s_mov_b32 m0, 0x20840
	s_nop 0
	global_load_lds_dwordx4 v250, s[90:91]
	s_mov_b32 m0, 0x20c40
	s_nop 0
	global_load_lds_dwordx4 v250, s[92:93]
	s_add_i32 s85, 0, 0x14000
	v_add_u32_e32 v192, s85, v170
	s_add_i32 s36, s84, s68
	ds_read_b128 v[200:203], v192
	ds_read_b128 v[204:207], v192 offset:1024
	ds_read_b128 v[208:211], v192 offset:2048
	ds_read_b128 v[222:225], v192 offset:3072
	v_lshl_add_u64 v[192:193], s[64:65], 0, v[164:165]
	s_mov_b32 m0, s36
	v_lshl_add_u64 v[214:215], s[64:65], 0, v[162:163]
	global_load_lds_dwordx4 v[192:193], off
	s_add_i32 m0, s36, 0x2000
	s_nop 0
	global_load_lds_dwordx4 v[214:215], off
	s_barrier
	s_waitcnt lgkmcnt(0)
	s_waitcnt lgkmcnt(0)
	v_mfma_f32_16x16x32_bf16 v[154:157], v[200:203], v[78:81], 0
	v_mfma_f32_16x16x32_bf16 v[78:81], v[208:211], v[78:81], 0
	v_mfma_f32_16x16x32_bf16 v[154:157], v[204:207], v[86:89], v[154:157]
	v_mfma_f32_16x16x32_bf16 v[78:81], v[222:225], v[86:89], v[78:81]
	v_mfma_f32_16x16x32_bf16 v[86:89], v[200:203], v[90:93], 0
	v_mfma_f32_16x16x32_bf16 v[90:93], v[208:211], v[90:93], 0
	v_mfma_f32_16x16x32_bf16 v[114:117], v[208:211], v[176:179], 0
	v_mfma_f32_16x16x32_bf16 v[106:109], v[200:203], v[184:187], 0
	v_mfma_f32_16x16x32_bf16 v[98:101], v[208:211], v[184:187], 0
	v_mfma_f32_16x16x32_bf16 v[86:89], v[204:207], v[94:97], v[86:89]
	v_mfma_f32_16x16x32_bf16 v[90:93], v[222:225], v[94:97], v[90:93]
	v_mfma_f32_16x16x32_bf16 v[94:97], v[200:203], v[176:179], 0
	v_mfma_f32_16x16x32_bf16 v[114:117], v[222:225], v[180:183], v[114:117]
	v_mfma_f32_16x16x32_bf16 v[106:109], v[204:207], v[188:191], v[106:109]
	v_mfma_f32_16x16x32_bf16 v[98:101], v[222:225], v[188:191], v[98:101]
	v_mfma_f32_16x16x32_bf16 v[94:97], v[204:207], v[180:183], v[94:97]
	s_mov_b32 m0, s69
	v_lshl_add_u64 v[234:235], s[66:67], 0, v[164:165]
	s_barrier
	ds_read_b128 v[122:125], v175 offset:16384
	ds_read_b128 v[130:133], v175 offset:17408
	ds_read_b128 v[138:141], v175 offset:18432
	ds_read_b128 v[146:149], v175 offset:19456
	ds_read_b128 v[176:179], v175 offset:20480
	ds_read_b128 v[180:183], v175 offset:21504
	ds_read_b128 v[184:187], v175 offset:22528
	ds_read_b128 v[188:191], v175 offset:23552
	global_load_lds_dwordx4 v[234:235], off
	v_lshl_add_u64 v[236:237], s[66:67], 0, v[162:163]
	s_mov_b32 m0, s70
	s_nop 0
	global_load_lds_dwordx4 v[236:237], off
	s_barrier
	s_waitcnt lgkmcnt(0)
	s_waitcnt lgkmcnt(0)
	v_mfma_f32_16x16x32_bf16 v[82:85], v[58:61], v[122:125], 0
	v_mfma_f32_16x16x32_bf16 v[54:57], v[66:69], v[122:125], 0
	v_mfma_f32_16x16x32_bf16 v[46:49], v[58:61], v[138:141], 0
	v_mfma_f32_16x16x32_bf16 v[38:41], v[66:69], v[138:141], 0
	v_mfma_f32_16x16x32_bf16 v[30:33], v[58:61], v[176:179], 0
	v_mfma_f32_16x16x32_bf16 v[22:25], v[66:69], v[176:179], 0
	v_mfma_f32_16x16x32_bf16 v[14:17], v[58:61], v[184:187], 0
	v_mfma_f32_16x16x32_bf16 v[6:9], v[66:69], v[184:187], 0
	v_mfma_f32_16x16x32_bf16 v[82:85], v[62:65], v[130:133], v[82:85]
	v_mfma_f32_16x16x32_bf16 v[54:57], v[70:73], v[130:133], v[54:57]
	v_mfma_f32_16x16x32_bf16 v[46:49], v[62:65], v[146:149], v[46:49]
	v_mfma_f32_16x16x32_bf16 v[38:41], v[70:73], v[146:149], v[38:41]
	v_mfma_f32_16x16x32_bf16 v[30:33], v[62:65], v[180:183], v[30:33]
	v_mfma_f32_16x16x32_bf16 v[22:25], v[70:73], v[180:183], v[22:25]
	v_mfma_f32_16x16x32_bf16 v[14:17], v[62:65], v[188:191], v[14:17]
	v_mfma_f32_16x16x32_bf16 v[6:9], v[70:73], v[188:191], v[6:9]
	s_barrier
	s_add_u32 s36, s64, 0x40000
	s_addc_u32 s37, s65, 0
	s_add_i32 s84, s85, s68
	v_lshl_add_u64 v[58:59], s[36:37], 0, v[164:165]
	s_mov_b32 m0, s84
	s_nop 0
	global_load_lds_dwordx4 v[58:59], off
	v_lshl_add_u64 v[58:59], s[36:37], 0, v[162:163]
	s_add_i32 m0, s84, 0x2000
	s_nop 0
	global_load_lds_dwordx4 v[58:59], off
	s_waitcnt vmcnt(6)
	s_barrier
	v_mfma_f32_16x16x32_bf16 v[50:53], v[208:211], v[122:125], 0
	v_mfma_f32_16x16x32_bf16 v[42:45], v[200:203], v[138:141], 0
	v_mfma_f32_16x16x32_bf16 v[34:37], v[208:211], v[138:141], 0
	v_mfma_f32_16x16x32_bf16 v[26:29], v[200:203], v[176:179], 0
	v_mfma_f32_16x16x32_bf16 v[18:21], v[208:211], v[176:179], 0
	v_mfma_f32_16x16x32_bf16 v[10:13], v[200:203], v[184:187], 0
	v_mfma_f32_16x16x32_bf16 v[2:5], v[208:211], v[184:187], 0
	v_mfma_f32_16x16x32_bf16 v[58:61], v[200:203], v[122:125], 0
	v_mfma_f32_16x16x32_bf16 v[50:53], v[222:225], v[130:133], v[50:53]
	v_mfma_f32_16x16x32_bf16 v[42:45], v[204:207], v[146:149], v[42:45]
	v_mfma_f32_16x16x32_bf16 v[34:37], v[222:225], v[146:149], v[34:37]
	v_mfma_f32_16x16x32_bf16 v[26:29], v[204:207], v[180:183], v[26:29]
	v_mfma_f32_16x16x32_bf16 v[18:21], v[222:225], v[180:183], v[18:21]
	v_mfma_f32_16x16x32_bf16 v[10:13], v[204:207], v[188:191], v[10:13]
	v_mfma_f32_16x16x32_bf16 v[2:5], v[222:225], v[188:191], v[2:5]
	v_mfma_f32_16x16x32_bf16 v[58:61], v[204:207], v[130:133], v[58:61]
	s_add_i32 s84, 0, 0x18000
	v_add_u32_e32 v74, s84, v170
	s_barrier
	ds_read_b128 v[62:65], v74
	ds_read_b128 v[66:69], v74 offset:1024
	ds_read_b128 v[70:73], v74 offset:2048
	ds_read_b128 v[74:77], v74 offset:3072
	s_add_u32 s36, s66, 0x40000
	s_addc_u32 s37, s67, 0
	s_mov_b32 m0, s71
	v_lshl_add_u64 v[138:139], s[36:37], 0, v[164:165]
	ds_read_b128 v[122:125], v175 offset:32768
	ds_read_b128 v[130:133], v175 offset:33792
	ds_read_b128 v[176:179], v175 offset:34816
	ds_read_b128 v[180:183], v175 offset:35840
	ds_read_b128 v[184:187], v175 offset:36864
	ds_read_b128 v[188:191], v175 offset:37888
	ds_read_b128 v[200:203], v175 offset:38912
	ds_read_b128 v[204:207], v175 offset:39936
	global_load_lds_dwordx4 v[138:139], off
	v_lshl_add_u64 v[138:139], s[36:37], 0, v[162:163]
	s_mov_b32 m0, s72
	s_nop 0
	global_load_lds_dwordx4 v[138:139], off
	s_waitcnt lgkmcnt(8)
	s_barrier
	s_waitcnt lgkmcnt(0)
	s_waitcnt lgkmcnt(0)
	v_mfma_f32_16x16x32_bf16 v[138:141], v[62:65], v[122:125], v[158:161]
	v_mfma_f32_16x16x32_bf16 v[158:161], v[66:69], v[130:133], v[138:141]
	v_mfma_f32_16x16x32_bf16 v[138:141], v[70:73], v[122:125], v[150:153]
	v_mfma_f32_16x16x32_bf16 v[150:153], v[74:77], v[130:133], v[138:141]
	v_mfma_f32_16x16x32_bf16 v[138:141], v[62:65], v[176:179], v[142:145]
	v_mfma_f32_16x16x32_bf16 v[134:137], v[70:73], v[176:179], v[134:137]
	v_mfma_f32_16x16x32_bf16 v[126:129], v[62:65], v[184:187], v[126:129]
	v_mfma_f32_16x16x32_bf16 v[118:121], v[70:73], v[184:187], v[118:121]
	v_mfma_f32_16x16x32_bf16 v[110:113], v[62:65], v[200:203], v[110:113]
	v_mfma_f32_16x16x32_bf16 v[102:105], v[70:73], v[200:203], v[102:105]
	v_mfma_f32_16x16x32_bf16 v[142:145], v[66:69], v[180:183], v[138:141]
	v_mfma_f32_16x16x32_bf16 v[134:137], v[74:77], v[180:183], v[134:137]
	v_mfma_f32_16x16x32_bf16 v[126:129], v[66:69], v[188:191], v[126:129]
	v_mfma_f32_16x16x32_bf16 v[118:121], v[74:77], v[188:191], v[118:121]
	v_mfma_f32_16x16x32_bf16 v[110:113], v[66:69], v[204:207], v[110:113]
	v_mfma_f32_16x16x32_bf16 v[102:105], v[74:77], v[204:207], v[102:105]
	s_barrier
	s_add_i32 s66, 0, 0x1c000
	v_add_u32_e32 v138, s66, v170
	s_add_i32 s36, s84, s68
	ds_read_b128 v[208:211], v138
	ds_read_b128 v[222:225], v138 offset:1024
	ds_read_b128 v[226:229], v138 offset:2048
	ds_read_b128 v[230:233], v138 offset:3072
	v_lshl_add_u64 v[138:139], v[192:193], 0, s[22:23]
	s_mov_b32 m0, s36
	s_nop 0
	global_load_lds_dwordx4 v[138:139], off
	v_lshl_add_u64 v[138:139], v[214:215], 0, s[22:23]
	s_add_i32 m0, s36, 0x2000
	s_nop 0
	global_load_lds_dwordx4 v[138:139], off
	s_barrier
	s_waitcnt lgkmcnt(0)
	s_waitcnt lgkmcnt(0)
	v_mfma_f32_16x16x32_bf16 v[78:81], v[226:229], v[122:125], v[78:81]
	v_mfma_f32_16x16x32_bf16 v[138:141], v[208:211], v[122:125], v[154:157]
	v_mfma_f32_16x16x32_bf16 v[146:149], v[230:233], v[130:133], v[78:81]
	v_mfma_f32_16x16x32_bf16 v[78:81], v[208:211], v[176:179], v[86:89]
	v_mfma_f32_16x16x32_bf16 v[154:157], v[222:225], v[130:133], v[138:141]
	v_mfma_f32_16x16x32_bf16 v[138:141], v[222:225], v[180:183], v[78:81]
	v_mfma_f32_16x16x32_bf16 v[78:81], v[226:229], v[176:179], v[90:93]
	v_mfma_f32_16x16x32_bf16 v[130:133], v[230:233], v[180:183], v[78:81]
	v_mfma_f32_16x16x32_bf16 v[78:81], v[208:211], v[184:187], v[94:97]
	v_mfma_f32_16x16x32_bf16 v[122:125], v[222:225], v[188:191], v[78:81]
	v_mfma_f32_16x16x32_bf16 v[78:81], v[226:229], v[184:187], v[114:117]
	v_mfma_f32_16x16x32_bf16 v[114:117], v[230:233], v[188:191], v[78:81]
	v_mfma_f32_16x16x32_bf16 v[78:81], v[208:211], v[200:203], v[106:109]
	v_mfma_f32_16x16x32_bf16 v[106:109], v[222:225], v[204:207], v[78:81]
	v_mfma_f32_16x16x32_bf16 v[78:81], v[226:229], v[200:203], v[98:101]
	v_mfma_f32_16x16x32_bf16 v[98:101], v[230:233], v[204:207], v[78:81]
	s_mov_b32 m0, s73
	v_lshl_add_u64 v[192:193], v[234:235], 0, s[22:23]
	s_barrier
	s_nop 2
	ds_read_b128 v[78:81], v175 offset:49152
	ds_read_b128 v[86:89], v175 offset:50176
	ds_read_b128 v[90:93], v175 offset:51200
	ds_read_b128 v[94:97], v175 offset:52224
	ds_read_b128 v[176:179], v175 offset:53248
	ds_read_b128 v[180:183], v175 offset:54272
	ds_read_b128 v[184:187], v175 offset:55296
	ds_read_b128 v[188:191], v175 offset:56320
	global_load_lds_dwordx4 v[192:193], off
	v_lshl_add_u64 v[192:193], v[236:237], 0, s[22:23]
	s_mov_b32 m0, s75
	s_nop 0
	global_load_lds_dwordx4 v[192:193], off
	s_barrier
	s_waitcnt lgkmcnt(0)
	s_waitcnt lgkmcnt(0)
	v_mfma_f32_16x16x32_bf16 v[82:85], v[62:65], v[78:81], v[82:85]
	v_mfma_f32_16x16x32_bf16 v[54:57], v[70:73], v[78:81], v[54:57]
	v_mfma_f32_16x16x32_bf16 v[46:49], v[62:65], v[90:93], v[46:49]
	v_mfma_f32_16x16x32_bf16 v[38:41], v[70:73], v[90:93], v[38:41]
	v_mfma_f32_16x16x32_bf16 v[30:33], v[62:65], v[176:179], v[30:33]
	v_mfma_f32_16x16x32_bf16 v[22:25], v[70:73], v[176:179], v[22:25]
	v_mfma_f32_16x16x32_bf16 v[14:17], v[62:65], v[184:187], v[14:17]
	v_mfma_f32_16x16x32_bf16 v[6:9], v[70:73], v[184:187], v[6:9]
	v_mfma_f32_16x16x32_bf16 v[82:85], v[66:69], v[86:89], v[82:85]
	v_mfma_f32_16x16x32_bf16 v[54:57], v[74:77], v[86:89], v[54:57]
	v_mfma_f32_16x16x32_bf16 v[46:49], v[66:69], v[94:97], v[46:49]
	v_mfma_f32_16x16x32_bf16 v[38:41], v[74:77], v[94:97], v[38:41]
	v_mfma_f32_16x16x32_bf16 v[30:33], v[66:69], v[180:183], v[30:33]
	v_mfma_f32_16x16x32_bf16 v[22:25], v[74:77], v[180:183], v[22:25]
	v_mfma_f32_16x16x32_bf16 v[14:17], v[66:69], v[188:191], v[14:17]
	v_mfma_f32_16x16x32_bf16 v[6:9], v[74:77], v[188:191], v[6:9]
	s_barrier
	s_add_u32 s36, s64, 0x40080
	s_addc_u32 s37, s65, 0
	s_add_i32 s64, s66, s68
	v_lshl_add_u64 v[62:63], s[36:37], 0, v[164:165]
	s_mov_b32 m0, s64
	s_nop 0
	global_load_lds_dwordx4 v[62:63], off
	v_lshl_add_u64 v[62:63], s[36:37], 0, v[162:163]
	s_add_i32 m0, s64, 0x2000
	s_nop 0
	global_load_lds_dwordx4 v[62:63], off
	s_waitcnt vmcnt(6)
	s_barrier
	v_mfma_f32_16x16x32_bf16 v[58:61], v[208:211], v[78:81], v[58:61]
	v_mfma_f32_16x16x32_bf16 v[50:53], v[226:229], v[78:81], v[50:53]
	v_mfma_f32_16x16x32_bf16 v[42:45], v[208:211], v[90:93], v[42:45]
	v_mfma_f32_16x16x32_bf16 v[34:37], v[226:229], v[90:93], v[34:37]
	v_mfma_f32_16x16x32_bf16 v[26:29], v[208:211], v[176:179], v[26:29]
	v_mfma_f32_16x16x32_bf16 v[18:21], v[226:229], v[176:179], v[18:21]
	v_mfma_f32_16x16x32_bf16 v[10:13], v[208:211], v[184:187], v[10:13]
	v_mfma_f32_16x16x32_bf16 v[2:5], v[226:229], v[184:187], v[2:5]
	v_mfma_f32_16x16x32_bf16 v[74:77], v[222:225], v[86:89], v[58:61]
	v_mfma_f32_16x16x32_bf16 v[50:53], v[230:233], v[86:89], v[50:53]
	v_mfma_f32_16x16x32_bf16 v[42:45], v[222:225], v[94:97], v[42:45]
	v_mfma_f32_16x16x32_bf16 v[34:37], v[230:233], v[94:97], v[34:37]
	v_mfma_f32_16x16x32_bf16 v[26:29], v[222:225], v[180:183], v[26:29]
	v_mfma_f32_16x16x32_bf16 v[18:21], v[230:233], v[180:183], v[18:21]
	v_mfma_f32_16x16x32_bf16 v[10:13], v[222:225], v[188:191], v[10:13]
	v_mfma_f32_16x16x32_bf16 v[2:5], v[230:233], v[188:191], v[2:5]
	s_add_i32 s83, s83, 2
	s_add_u32 s81, s81, 0x100
	s_addc_u32 s82, s82, 0
	s_cmp_gt_u32 s83, 13
	s_mov_b64 s[36:37], s[62:63]
	s_barrier
	s_nop 0
	s_nop 0
	s_nop 0
	s_nop 0
	s_nop 0
	s_nop 0
	s_nop 0
	s_nop 0
	s_nop 0
	s_nop 0
	s_nop 0
	s_nop 0
